# loop-edge cleanup in hipcc inproj/up 8-phase loops: drop back-to-back s_setprio 0/1 pairs and the redundant second lgkmcnt(0) after the barrier
# speedup vs baseline: 1.0005x; 1.0005x over previous
.LBB0_76:
	s_add_u32 s88, s46, 0xfffc0080
	s_addc_u32 s89, s47, -1
	s_add_i32 s92, 0, 0x10000
	v_add_u32_e32 v78, s92, v214
	v_add_u32_e32 v158, s28, v214
	ds_read_b128 v[66:69], v78
	ds_read_b128 v[70:73], v78 offset:1024
	ds_read_b128 v[74:77], v78 offset:2048
	ds_read_b128 v[78:81], v78 offset:3072
	ds_read_b128 v[82:85], v158
	ds_read_b128 v[86:89], v158 offset:1024
	ds_read_b128 v[154:157], v158 offset:2048
	ds_read_b128 v[158:161], v158 offset:3072
	s_cmp_eq_u32 s18, 12
	s_cselect_b32 vcc_hi, s13, s89
	s_cselect_b32 vcc_lo, s15, s88
	s_cselect_b32 s89, s19, s85
	s_cselect_b32 s88, s80, s81
	v_lshl_add_u64 v[166:167], s[46:47], 0, v[182:183]
	s_add_i32 m0, s87, 0xc000
	ds_read_b128 v[184:187], v220
	ds_read_b128 v[188:191], v220 offset:1024
	ds_read_b128 v[222:225], v220 offset:2048
	ds_read_b128 v[226:229], v220 offset:3072
	ds_read_b128 v[230:233], v220 offset:4096
	ds_read_b128 v[234:237], v220 offset:5120
	ds_read_b128 v[238:241], v220 offset:6144
	ds_read_b128 v[242:245], v220 offset:7168
	global_load_lds_dwordx4 v[166:167], off
	v_lshl_add_u64 v[166:167], s[46:47], 0, v[180:181]
	s_add_i32 m0, s87, 0xe000
	s_nop 0
	global_load_lds_dwordx4 v[166:167], off
	s_waitcnt vmcnt(8)
	s_waitcnt lgkmcnt(0)
	s_barrier
	s_setprio 1
	v_mfma_f32_16x16x32_bf16 v[134:137], v[66:69], v[184:187], v[134:137]
	v_mfma_f32_16x16x32_bf16 v[122:125], v[74:77], v[184:187], v[122:125]
	v_mfma_f32_16x16x32_bf16 v[142:145], v[66:69], v[222:225], v[142:145]
	v_mfma_f32_16x16x32_bf16 v[130:133], v[74:77], v[222:225], v[130:133]
	v_mfma_f32_16x16x32_bf16 v[110:113], v[66:69], v[230:233], v[110:113]
	v_mfma_f32_16x16x32_bf16 v[106:109], v[74:77], v[230:233], v[106:109]
	v_mfma_f32_16x16x32_bf16 v[94:97], v[66:69], v[238:241], v[94:97]
	v_mfma_f32_16x16x32_bf16 v[90:93], v[74:77], v[238:241], v[90:93]
	v_mfma_f32_16x16x32_bf16 v[134:137], v[70:73], v[188:191], v[134:137]
	v_mfma_f32_16x16x32_bf16 v[122:125], v[78:81], v[188:191], v[122:125]
	v_mfma_f32_16x16x32_bf16 v[142:145], v[70:73], v[226:229], v[142:145]
	v_mfma_f32_16x16x32_bf16 v[130:133], v[78:81], v[226:229], v[130:133]
	v_mfma_f32_16x16x32_bf16 v[110:113], v[70:73], v[234:237], v[110:113]
	v_mfma_f32_16x16x32_bf16 v[106:109], v[78:81], v[234:237], v[106:109]
	v_mfma_f32_16x16x32_bf16 v[94:97], v[70:73], v[242:245], v[94:97]
	v_mfma_f32_16x16x32_bf16 v[90:93], v[78:81], v[242:245], v[90:93]
	v_mfma_f32_16x16x32_bf16 v[150:153], v[82:85], v[184:187], v[150:153]
	v_mfma_f32_16x16x32_bf16 v[146:149], v[154:157], v[184:187], v[146:149]
	v_mfma_f32_16x16x32_bf16 v[138:141], v[82:85], v[222:225], v[138:141]
	v_mfma_f32_16x16x32_bf16 v[126:129], v[154:157], v[222:225], v[126:129]
	v_mfma_f32_16x16x32_bf16 v[118:121], v[82:85], v[230:233], v[118:121]
	v_mfma_f32_16x16x32_bf16 v[114:117], v[154:157], v[230:233], v[114:117]
	v_mfma_f32_16x16x32_bf16 v[102:105], v[82:85], v[238:241], v[102:105]
	v_mfma_f32_16x16x32_bf16 v[98:101], v[154:157], v[238:241], v[98:101]
	v_mfma_f32_16x16x32_bf16 v[150:153], v[86:89], v[188:191], v[150:153]
	v_mfma_f32_16x16x32_bf16 v[146:149], v[158:161], v[188:191], v[146:149]
	v_mfma_f32_16x16x32_bf16 v[138:141], v[86:89], v[226:229], v[138:141]
	v_mfma_f32_16x16x32_bf16 v[126:129], v[158:161], v[226:229], v[126:129]
	v_mfma_f32_16x16x32_bf16 v[118:121], v[86:89], v[234:237], v[118:121]
	v_mfma_f32_16x16x32_bf16 v[114:117], v[158:161], v[234:237], v[114:117]
	v_mfma_f32_16x16x32_bf16 v[102:105], v[86:89], v[242:245], v[102:105]
	v_mfma_f32_16x16x32_bf16 v[98:101], v[158:161], v[242:245], v[98:101]
	s_setprio 0
	s_barrier
	s_add_i32 s92, s92, s48
	v_lshl_add_u64 v[166:167], s[88:89], 0, v[162:163]
	s_mov_b32 m0, s92
	ds_read_b128 v[184:187], v220 offset:16384
	ds_read_b128 v[188:191], v220 offset:17408
	ds_read_b128 v[222:225], v220 offset:18432
	ds_read_b128 v[226:229], v220 offset:19456
	ds_read_b128 v[230:233], v220 offset:20480
	ds_read_b128 v[234:237], v220 offset:21504
	ds_read_b128 v[238:241], v220 offset:22528
	ds_read_b128 v[242:245], v220 offset:23552
	global_load_lds_dwordx4 v[166:167], off
	s_add_i32 m0, s92, 0x2000
	s_add_u32 s92, s88, 0x40000
	v_lshl_add_u64 v[192:193], s[88:89], 0, v[178:179]
	s_addc_u32 s93, s89, 0
	s_add_i32 s17, s28, s48
	global_load_lds_dwordx4 v[192:193], off
	v_lshl_add_u64 v[246:247], s[92:93], 0, v[162:163]
	s_mov_b32 m0, s17
	v_lshl_add_u64 v[248:249], vcc, 0, v[176:177]
	global_load_lds_dwordx4 v[246:247], off
	v_lshl_add_u64 v[246:247], s[92:93], 0, v[178:179]
	s_add_i32 m0, s17, 0x2000
	s_nop 0
	global_load_lds_dwordx4 v[246:247], off
	v_lshl_add_u64 v[246:247], vcc, 0, v[174:175]
	s_mov_b32 m0, s87
	s_nop 0
	global_load_lds_dwordx4 v[246:247], off
	s_mov_b32 m0, s42
	s_nop 0
	global_load_lds_dwordx4 v[248:249], off
	s_waitcnt vmcnt(8)
	s_waitcnt lgkmcnt(0)
	s_barrier
	s_setprio 1
	v_mfma_f32_16x16x32_bf16 v[50:53], v[66:69], v[184:187], v[50:53]
	v_mfma_f32_16x16x32_bf16 v[34:37], v[74:77], v[184:187], v[34:37]
	v_mfma_f32_16x16x32_bf16 v[54:57], v[66:69], v[222:225], v[54:57]
	v_mfma_f32_16x16x32_bf16 v[46:49], v[74:77], v[222:225], v[46:49]
	v_mfma_f32_16x16x32_bf16 v[22:25], v[66:69], v[230:233], v[22:25]
	v_mfma_f32_16x16x32_bf16 v[18:21], v[74:77], v[230:233], v[18:21]
	v_mfma_f32_16x16x32_bf16 v[10:13], v[66:69], v[238:241], v[10:13]
	v_mfma_f32_16x16x32_bf16 v[2:5], v[74:77], v[238:241], v[2:5]
	v_mfma_f32_16x16x32_bf16 v[50:53], v[70:73], v[188:191], v[50:53]
	v_mfma_f32_16x16x32_bf16 v[34:37], v[78:81], v[188:191], v[34:37]
	v_mfma_f32_16x16x32_bf16 v[54:57], v[70:73], v[226:229], v[54:57]
	v_mfma_f32_16x16x32_bf16 v[46:49], v[78:81], v[226:229], v[46:49]
	v_mfma_f32_16x16x32_bf16 v[22:25], v[70:73], v[234:237], v[22:25]
	v_mfma_f32_16x16x32_bf16 v[18:21], v[78:81], v[234:237], v[18:21]
	v_mfma_f32_16x16x32_bf16 v[10:13], v[70:73], v[242:245], v[10:13]
	v_mfma_f32_16x16x32_bf16 v[2:5], v[78:81], v[242:245], v[2:5]
	v_mfma_f32_16x16x32_bf16 v[62:65], v[82:85], v[184:187], v[62:65]
	v_mfma_f32_16x16x32_bf16 v[58:61], v[154:157], v[184:187], v[58:61]
	v_mfma_f32_16x16x32_bf16 v[42:45], v[82:85], v[222:225], v[42:45]
	v_mfma_f32_16x16x32_bf16 v[38:41], v[154:157], v[222:225], v[38:41]
	v_mfma_f32_16x16x32_bf16 v[30:33], v[82:85], v[230:233], v[30:33]
	v_mfma_f32_16x16x32_bf16 v[26:29], v[154:157], v[230:233], v[26:29]
	v_mfma_f32_16x16x32_bf16 v[14:17], v[82:85], v[238:241], v[14:17]
	v_mfma_f32_16x16x32_bf16 v[6:9], v[154:157], v[238:241], v[6:9]
	v_mfma_f32_16x16x32_bf16 v[62:65], v[86:89], v[188:191], v[62:65]
	v_mfma_f32_16x16x32_bf16 v[58:61], v[158:161], v[188:191], v[58:61]
	v_mfma_f32_16x16x32_bf16 v[42:45], v[86:89], v[226:229], v[42:45]
	v_mfma_f32_16x16x32_bf16 v[38:41], v[158:161], v[226:229], v[38:41]
	v_mfma_f32_16x16x32_bf16 v[30:33], v[86:89], v[234:237], v[30:33]
	v_mfma_f32_16x16x32_bf16 v[26:29], v[158:161], v[234:237], v[26:29]
	v_mfma_f32_16x16x32_bf16 v[14:17], v[86:89], v[242:245], v[14:17]
	v_mfma_f32_16x16x32_bf16 v[6:9], v[158:161], v[242:245], v[6:9]
	s_setprio 0
	s_barrier
	s_add_i32 s17, 0, 0x18000
	s_add_i32 s1, 0, 0x1c000
	v_add_u32_e32 v78, s17, v214
	v_add_u32_e32 v158, s1, v214
	ds_read_b128 v[66:69], v78
	ds_read_b128 v[70:73], v78 offset:1024
	ds_read_b128 v[74:77], v78 offset:2048
	ds_read_b128 v[78:81], v78 offset:3072
	ds_read_b128 v[82:85], v158
	ds_read_b128 v[86:89], v158 offset:1024
	ds_read_b128 v[154:157], v158 offset:2048
	ds_read_b128 v[158:161], v158 offset:3072
	s_add_u32 s92, vcc_lo, 0x40000
	s_addc_u32 s93, vcc_hi, 0
	s_mov_b32 m0, s43
	v_lshl_add_u64 v[250:251], s[92:93], 0, v[174:175]
	ds_read_b128 v[184:187], v220 offset:32768
	ds_read_b128 v[188:191], v220 offset:33792
	ds_read_b128 v[222:225], v220 offset:34816
	ds_read_b128 v[226:229], v220 offset:35840
	ds_read_b128 v[230:233], v220 offset:36864
	ds_read_b128 v[234:237], v220 offset:37888
	ds_read_b128 v[238:241], v220 offset:38912
	ds_read_b128 v[242:245], v220 offset:39936
	global_load_lds_dwordx4 v[250:251], off
	v_lshl_add_u64 v[250:251], s[92:93], 0, v[176:177]
	s_mov_b32 m0, s36
	s_nop 0
	global_load_lds_dwordx4 v[250:251], off
	s_waitcnt vmcnt(8)
	s_waitcnt lgkmcnt(0)
	s_barrier
	s_setprio 1
	v_mfma_f32_16x16x32_bf16 v[134:137], v[66:69], v[184:187], v[134:137]
	v_mfma_f32_16x16x32_bf16 v[122:125], v[74:77], v[184:187], v[122:125]
	v_mfma_f32_16x16x32_bf16 v[142:145], v[66:69], v[222:225], v[142:145]
	v_mfma_f32_16x16x32_bf16 v[130:133], v[74:77], v[222:225], v[130:133]
	v_mfma_f32_16x16x32_bf16 v[110:113], v[66:69], v[230:233], v[110:113]
	v_mfma_f32_16x16x32_bf16 v[106:109], v[74:77], v[230:233], v[106:109]
	v_mfma_f32_16x16x32_bf16 v[94:97], v[66:69], v[238:241], v[94:97]
	v_mfma_f32_16x16x32_bf16 v[90:93], v[74:77], v[238:241], v[90:93]
	v_mfma_f32_16x16x32_bf16 v[134:137], v[70:73], v[188:191], v[134:137]
	v_mfma_f32_16x16x32_bf16 v[122:125], v[78:81], v[188:191], v[122:125]
	v_mfma_f32_16x16x32_bf16 v[142:145], v[70:73], v[226:229], v[142:145]
	v_mfma_f32_16x16x32_bf16 v[130:133], v[78:81], v[226:229], v[130:133]
	v_mfma_f32_16x16x32_bf16 v[110:113], v[70:73], v[234:237], v[110:113]
	v_mfma_f32_16x16x32_bf16 v[106:109], v[78:81], v[234:237], v[106:109]
	v_mfma_f32_16x16x32_bf16 v[94:97], v[70:73], v[242:245], v[94:97]
	v_mfma_f32_16x16x32_bf16 v[90:93], v[78:81], v[242:245], v[90:93]
	v_mfma_f32_16x16x32_bf16 v[150:153], v[82:85], v[184:187], v[150:153]
	v_mfma_f32_16x16x32_bf16 v[146:149], v[154:157], v[184:187], v[146:149]
	v_mfma_f32_16x16x32_bf16 v[138:141], v[82:85], v[222:225], v[138:141]
	v_mfma_f32_16x16x32_bf16 v[126:129], v[154:157], v[222:225], v[126:129]
	v_mfma_f32_16x16x32_bf16 v[118:121], v[82:85], v[230:233], v[118:121]
	v_mfma_f32_16x16x32_bf16 v[114:117], v[154:157], v[230:233], v[114:117]
	v_mfma_f32_16x16x32_bf16 v[102:105], v[82:85], v[238:241], v[102:105]
	v_mfma_f32_16x16x32_bf16 v[98:101], v[154:157], v[238:241], v[98:101]
	v_mfma_f32_16x16x32_bf16 v[150:153], v[86:89], v[188:191], v[150:153]
	v_mfma_f32_16x16x32_bf16 v[146:149], v[158:161], v[188:191], v[146:149]
	v_mfma_f32_16x16x32_bf16 v[138:141], v[86:89], v[226:229], v[138:141]
	v_mfma_f32_16x16x32_bf16 v[126:129], v[158:161], v[226:229], v[126:129]
	v_mfma_f32_16x16x32_bf16 v[118:121], v[86:89], v[234:237], v[118:121]
	v_mfma_f32_16x16x32_bf16 v[114:117], v[158:161], v[234:237], v[114:117]
	v_mfma_f32_16x16x32_bf16 v[102:105], v[86:89], v[242:245], v[102:105]
	v_mfma_f32_16x16x32_bf16 v[98:101], v[158:161], v[242:245], v[98:101]
	s_setprio 0
	s_barrier
	s_add_i32 s17, s17, s48
	v_lshl_add_u64 v[166:167], v[166:167], 0, s[26:27]
	s_mov_b32 m0, s17
	ds_read_b128 v[184:187], v220 offset:49152
	ds_read_b128 v[188:191], v220 offset:50176
	ds_read_b128 v[222:225], v220 offset:51200
	ds_read_b128 v[226:229], v220 offset:52224
	ds_read_b128 v[230:233], v220 offset:53248
	ds_read_b128 v[234:237], v220 offset:54272
	ds_read_b128 v[238:241], v220 offset:55296
	ds_read_b128 v[242:245], v220 offset:56320
	global_load_lds_dwordx4 v[166:167], off
	s_add_i32 m0, s17, 0x2000
	s_add_u32 s88, s88, 0x40080
	v_lshl_add_u64 v[166:167], v[192:193], 0, s[26:27]
	s_addc_u32 s89, s89, 0
	s_add_i32 s1, s1, s48
	global_load_lds_dwordx4 v[166:167], off
	v_lshl_add_u64 v[166:167], s[88:89], 0, v[162:163]
	s_mov_b32 m0, s1
	s_nop 0
	global_load_lds_dwordx4 v[166:167], off
	v_lshl_add_u64 v[166:167], s[88:89], 0, v[178:179]
	s_add_i32 m0, s1, 0x2000
	s_nop 0
	global_load_lds_dwordx4 v[166:167], off
	v_lshl_add_u64 v[166:167], v[246:247], 0, s[26:27]
	s_mov_b32 m0, s37
	s_nop 0
	global_load_lds_dwordx4 v[166:167], off
	v_lshl_add_u64 v[166:167], v[248:249], 0, s[26:27]
	s_mov_b32 m0, s0
	s_nop 0
	global_load_lds_dwordx4 v[166:167], off
	s_waitcnt vmcnt(8)
	s_waitcnt lgkmcnt(0)
	s_barrier
	s_setprio 1
	v_mfma_f32_16x16x32_bf16 v[50:53], v[66:69], v[184:187], v[50:53]
	v_mfma_f32_16x16x32_bf16 v[34:37], v[74:77], v[184:187], v[34:37]
	v_mfma_f32_16x16x32_bf16 v[54:57], v[66:69], v[222:225], v[54:57]
	v_mfma_f32_16x16x32_bf16 v[46:49], v[74:77], v[222:225], v[46:49]
	v_mfma_f32_16x16x32_bf16 v[22:25], v[66:69], v[230:233], v[22:25]
	v_mfma_f32_16x16x32_bf16 v[18:21], v[74:77], v[230:233], v[18:21]
	v_mfma_f32_16x16x32_bf16 v[10:13], v[66:69], v[238:241], v[10:13]
	v_mfma_f32_16x16x32_bf16 v[2:5], v[74:77], v[238:241], v[2:5]
	v_mfma_f32_16x16x32_bf16 v[50:53], v[70:73], v[188:191], v[50:53]
	v_mfma_f32_16x16x32_bf16 v[34:37], v[78:81], v[188:191], v[34:37]
	v_mfma_f32_16x16x32_bf16 v[54:57], v[70:73], v[226:229], v[54:57]
	v_mfma_f32_16x16x32_bf16 v[46:49], v[78:81], v[226:229], v[46:49]
	v_mfma_f32_16x16x32_bf16 v[22:25], v[70:73], v[234:237], v[22:25]
	v_mfma_f32_16x16x32_bf16 v[18:21], v[78:81], v[234:237], v[18:21]
	v_mfma_f32_16x16x32_bf16 v[10:13], v[70:73], v[242:245], v[10:13]
	v_mfma_f32_16x16x32_bf16 v[2:5], v[78:81], v[242:245], v[2:5]
	v_mfma_f32_16x16x32_bf16 v[62:65], v[82:85], v[184:187], v[62:65]
	v_mfma_f32_16x16x32_bf16 v[58:61], v[154:157], v[184:187], v[58:61]
	v_mfma_f32_16x16x32_bf16 v[42:45], v[82:85], v[222:225], v[42:45]
	v_mfma_f32_16x16x32_bf16 v[38:41], v[154:157], v[222:225], v[38:41]
	v_mfma_f32_16x16x32_bf16 v[30:33], v[82:85], v[230:233], v[30:33]
	v_mfma_f32_16x16x32_bf16 v[26:29], v[154:157], v[230:233], v[26:29]
	v_mfma_f32_16x16x32_bf16 v[14:17], v[82:85], v[238:241], v[14:17]
	v_mfma_f32_16x16x32_bf16 v[6:9], v[154:157], v[238:241], v[6:9]
	v_mfma_f32_16x16x32_bf16 v[62:65], v[86:89], v[188:191], v[62:65]
	v_mfma_f32_16x16x32_bf16 v[58:61], v[158:161], v[188:191], v[58:61]
	v_mfma_f32_16x16x32_bf16 v[42:45], v[86:89], v[226:229], v[42:45]
	v_mfma_f32_16x16x32_bf16 v[38:41], v[158:161], v[226:229], v[38:41]
	v_mfma_f32_16x16x32_bf16 v[30:33], v[86:89], v[234:237], v[30:33]
	v_mfma_f32_16x16x32_bf16 v[26:29], v[158:161], v[234:237], v[26:29]
	v_mfma_f32_16x16x32_bf16 v[14:17], v[86:89], v[242:245], v[14:17]
	v_mfma_f32_16x16x32_bf16 v[6:9], v[158:161], v[242:245], v[6:9]
	s_setprio 0
	s_barrier
	s_add_i32 s18, s18, 2
	s_add_u32 s81, s81, 0x100
	s_addc_u32 s85, s85, 0
	s_add_u32 s46, s46, 0x100
	s_addc_u32 s47, s47, 0
	s_cmp_gt_u32 s18, 13
	s_cbranch_scc0 .LBB0_76
	v_readlane_b32 s18, v252, 17
	v_readlane_b32 s19, v252, 18
	s_and_b64 vcc, exec, s[18:19]
	s_cbranch_vccz .LBB0_79
	s_barrier

.LBB0_416:
	s_add_u32 s30, s14, 0xfffc0080
	s_addc_u32 s31, s15, -1
	s_add_i32 s44, 0, 0x10000
	v_add_u32_e32 v162, s44, v143
	ds_read_b128 v[130:133], v162
	ds_read_b128 v[150:153], v162 offset:1024
	ds_read_b128 v[158:161], v162 offset:2048
	ds_read_b128 v[174:177], v162 offset:3072
	v_add_u32_e32 v162, s28, v143
	ds_read_b128 v[178:181], v162
	ds_read_b128 v[182:185], v162 offset:1024
	ds_read_b128 v[186:189], v162 offset:2048
	ds_read_b128 v[190:193], v162 offset:3072
	s_cmp_eq_u32 s43, 12
	s_cselect_b32 s41, s0, s31
	s_cselect_b32 s40, s3, s30
	s_cselect_b32 s31, s13, s42
	s_cselect_b32 s30, s17, s19
	v_lshl_add_u64 v[244:245], s[14:15], 0, v[148:149]
	s_add_i32 m0, s21, 0xc000
	ds_read_b128 v[212:215], v157
	ds_read_b128 v[216:219], v157 offset:1024
	ds_read_b128 v[220:223], v157 offset:2048
	ds_read_b128 v[224:227], v157 offset:3072
	ds_read_b128 v[228:231], v157 offset:4096
	ds_read_b128 v[232:235], v157 offset:5120
	ds_read_b128 v[236:239], v157 offset:6144
	ds_read_b128 v[240:243], v157 offset:7168
	global_load_lds_dwordx4 v[244:245], off
	v_lshl_add_u64 v[244:245], s[14:15], 0, v[146:147]
	s_add_i32 m0, s21, 0xe000
	s_nop 0
	global_load_lds_dwordx4 v[244:245], off
	s_waitcnt vmcnt(8)
	s_waitcnt lgkmcnt(0)
	s_barrier
	s_setprio 1
	v_mfma_f32_16x16x32_bf16 v[126:129], v[130:133], v[212:215], v[126:129]
	v_mfma_f32_16x16x32_bf16 v[122:125], v[158:161], v[212:215], v[122:125]
	v_mfma_f32_16x16x32_bf16 v[110:113], v[130:133], v[220:223], v[110:113]
	v_mfma_f32_16x16x32_bf16 v[106:109], v[158:161], v[220:223], v[106:109]
	v_mfma_f32_16x16x32_bf16 v[94:97], v[130:133], v[228:231], v[94:97]
	v_mfma_f32_16x16x32_bf16 v[90:93], v[158:161], v[228:231], v[90:93]
	v_mfma_f32_16x16x32_bf16 v[78:81], v[130:133], v[236:239], v[78:81]
	v_mfma_f32_16x16x32_bf16 v[74:77], v[158:161], v[236:239], v[74:77]
	v_mfma_f32_16x16x32_bf16 v[126:129], v[150:153], v[216:219], v[126:129]
	v_mfma_f32_16x16x32_bf16 v[122:125], v[174:177], v[216:219], v[122:125]
	v_mfma_f32_16x16x32_bf16 v[110:113], v[150:153], v[224:227], v[110:113]
	v_mfma_f32_16x16x32_bf16 v[106:109], v[174:177], v[224:227], v[106:109]
	v_mfma_f32_16x16x32_bf16 v[94:97], v[150:153], v[232:235], v[94:97]
	v_mfma_f32_16x16x32_bf16 v[90:93], v[174:177], v[232:235], v[90:93]
	v_mfma_f32_16x16x32_bf16 v[78:81], v[150:153], v[240:243], v[78:81]
	v_mfma_f32_16x16x32_bf16 v[74:77], v[174:177], v[240:243], v[74:77]
	v_mfma_f32_16x16x32_bf16 v[118:121], v[178:181], v[212:215], v[118:121]
	v_mfma_f32_16x16x32_bf16 v[114:117], v[186:189], v[212:215], v[114:117]
	v_mfma_f32_16x16x32_bf16 v[102:105], v[178:181], v[220:223], v[102:105]
	v_mfma_f32_16x16x32_bf16 v[98:101], v[186:189], v[220:223], v[98:101]
	v_mfma_f32_16x16x32_bf16 v[86:89], v[178:181], v[228:231], v[86:89]
	v_mfma_f32_16x16x32_bf16 v[82:85], v[186:189], v[228:231], v[82:85]
	v_mfma_f32_16x16x32_bf16 v[70:73], v[178:181], v[236:239], v[70:73]
	v_mfma_f32_16x16x32_bf16 v[66:69], v[186:189], v[236:239], v[66:69]
	v_mfma_f32_16x16x32_bf16 v[118:121], v[182:185], v[216:219], v[118:121]
	v_mfma_f32_16x16x32_bf16 v[114:117], v[190:193], v[216:219], v[114:117]
	v_mfma_f32_16x16x32_bf16 v[102:105], v[182:185], v[224:227], v[102:105]
	v_mfma_f32_16x16x32_bf16 v[98:101], v[190:193], v[224:227], v[98:101]
	v_mfma_f32_16x16x32_bf16 v[86:89], v[182:185], v[232:235], v[86:89]
	v_mfma_f32_16x16x32_bf16 v[82:85], v[190:193], v[232:235], v[82:85]
	v_mfma_f32_16x16x32_bf16 v[70:73], v[182:185], v[240:243], v[70:73]
	v_mfma_f32_16x16x32_bf16 v[66:69], v[190:193], v[240:243], v[66:69]
	s_setprio 0
	s_barrier
	s_add_i32 s44, s44, s20
	v_lshl_add_u64 v[244:245], s[30:31], 0, v[136:137]
	s_mov_b32 m0, s44
	ds_read_b128 v[212:215], v157 offset:16384
	ds_read_b128 v[216:219], v157 offset:17408
	ds_read_b128 v[220:223], v157 offset:18432
	ds_read_b128 v[224:227], v157 offset:19456
	ds_read_b128 v[228:231], v157 offset:20480
	ds_read_b128 v[232:235], v157 offset:21504
	ds_read_b128 v[236:239], v157 offset:22528
	ds_read_b128 v[240:243], v157 offset:23552
	global_load_lds_dwordx4 v[244:245], off
	s_add_i32 m0, s44, 0x2000
	s_add_u32 s44, s30, 0x40000
	v_lshl_add_u64 v[246:247], s[30:31], 0, v[140:141]
	s_addc_u32 s45, s31, 0
	s_add_i32 s48, s28, s20
	global_load_lds_dwordx4 v[246:247], off
	v_lshl_add_u64 v[248:249], s[44:45], 0, v[136:137]
	s_mov_b32 m0, s48
	v_lshl_add_u64 v[250:251], s[40:41], 0, v[138:139]
	global_load_lds_dwordx4 v[248:249], off
	v_lshl_add_u64 v[248:249], s[44:45], 0, v[140:141]
	s_add_i32 m0, s48, 0x2000
	s_nop 0
	global_load_lds_dwordx4 v[248:249], off
	v_lshl_add_u64 v[248:249], s[40:41], 0, v[134:135]
	s_mov_b32 m0, s21
	s_nop 0
	global_load_lds_dwordx4 v[248:249], off
	s_mov_b32 m0, s94
	s_nop 0
	global_load_lds_dwordx4 v[250:251], off
	s_waitcnt vmcnt(8)
	s_waitcnt lgkmcnt(0)
	s_barrier
	s_setprio 1
	v_mfma_f32_16x16x32_bf16 v[62:65], v[130:133], v[212:215], v[62:65]
	v_mfma_f32_16x16x32_bf16 v[58:61], v[158:161], v[212:215], v[58:61]
	v_mfma_f32_16x16x32_bf16 v[46:49], v[130:133], v[220:223], v[46:49]
	v_mfma_f32_16x16x32_bf16 v[42:45], v[158:161], v[220:223], v[42:45]
	v_mfma_f32_16x16x32_bf16 v[30:33], v[130:133], v[228:231], v[30:33]
	v_mfma_f32_16x16x32_bf16 v[26:29], v[158:161], v[228:231], v[26:29]
	v_mfma_f32_16x16x32_bf16 v[14:17], v[130:133], v[236:239], v[14:17]
	v_mfma_f32_16x16x32_bf16 v[10:13], v[158:161], v[236:239], v[10:13]
	v_mfma_f32_16x16x32_bf16 v[62:65], v[150:153], v[216:219], v[62:65]
	v_mfma_f32_16x16x32_bf16 v[58:61], v[174:177], v[216:219], v[58:61]
	v_mfma_f32_16x16x32_bf16 v[46:49], v[150:153], v[224:227], v[46:49]
	v_mfma_f32_16x16x32_bf16 v[42:45], v[174:177], v[224:227], v[42:45]
	v_mfma_f32_16x16x32_bf16 v[30:33], v[150:153], v[232:235], v[30:33]
	v_mfma_f32_16x16x32_bf16 v[26:29], v[174:177], v[232:235], v[26:29]
	v_mfma_f32_16x16x32_bf16 v[14:17], v[150:153], v[240:243], v[14:17]
	v_mfma_f32_16x16x32_bf16 v[10:13], v[174:177], v[240:243], v[10:13]
	v_mfma_f32_16x16x32_bf16 v[54:57], v[178:181], v[212:215], v[54:57]
	v_mfma_f32_16x16x32_bf16 v[50:53], v[186:189], v[212:215], v[50:53]
	v_mfma_f32_16x16x32_bf16 v[38:41], v[178:181], v[220:223], v[38:41]
	v_mfma_f32_16x16x32_bf16 v[34:37], v[186:189], v[220:223], v[34:37]
	v_mfma_f32_16x16x32_bf16 v[22:25], v[178:181], v[228:231], v[22:25]
	v_mfma_f32_16x16x32_bf16 v[18:21], v[186:189], v[228:231], v[18:21]
	v_mfma_f32_16x16x32_bf16 v[6:9], v[178:181], v[236:239], v[6:9]
	v_mfma_f32_16x16x32_bf16 v[2:5], v[186:189], v[236:239], v[2:5]
	v_mfma_f32_16x16x32_bf16 v[54:57], v[182:185], v[216:219], v[54:57]
	v_mfma_f32_16x16x32_bf16 v[50:53], v[190:193], v[216:219], v[50:53]
	v_mfma_f32_16x16x32_bf16 v[38:41], v[182:185], v[224:227], v[38:41]
	v_mfma_f32_16x16x32_bf16 v[34:37], v[190:193], v[224:227], v[34:37]
	v_mfma_f32_16x16x32_bf16 v[22:25], v[182:185], v[232:235], v[22:25]
	v_mfma_f32_16x16x32_bf16 v[18:21], v[190:193], v[232:235], v[18:21]
	v_mfma_f32_16x16x32_bf16 v[6:9], v[182:185], v[240:243], v[6:9]
	v_mfma_f32_16x16x32_bf16 v[2:5], v[190:193], v[240:243], v[2:5]
	s_setprio 0
	s_barrier
	s_add_i32 s44, 0, 0x18000
	v_add_u32_e32 v162, s44, v143
	s_add_i32 s45, 0, 0x1c000
	ds_read_b128 v[130:133], v162
	ds_read_b128 v[150:153], v162 offset:1024
	ds_read_b128 v[158:161], v162 offset:2048
	ds_read_b128 v[174:177], v162 offset:3072
	v_add_u32_e32 v162, s45, v143
	ds_read_b128 v[178:181], v162
	ds_read_b128 v[182:185], v162 offset:1024
	ds_read_b128 v[186:189], v162 offset:2048
	ds_read_b128 v[190:193], v162 offset:3072
	s_add_u32 s40, s40, 0x40000
	s_addc_u32 s41, s41, 0
	s_mov_b32 m0, s95
	v_lshl_add_u64 v[166:167], s[40:41], 0, v[134:135]
	ds_read_b128 v[212:215], v157 offset:32768
	ds_read_b128 v[216:219], v157 offset:33792
	ds_read_b128 v[220:223], v157 offset:34816
	ds_read_b128 v[224:227], v157 offset:35840
	ds_read_b128 v[228:231], v157 offset:36864
	ds_read_b128 v[232:235], v157 offset:37888
	ds_read_b128 v[236:239], v157 offset:38912
	ds_read_b128 v[240:243], v157 offset:39936
	global_load_lds_dwordx4 v[166:167], off
	v_lshl_add_u64 v[166:167], s[40:41], 0, v[138:139]
	s_mov_b32 m0, s96
	s_nop 0
	global_load_lds_dwordx4 v[166:167], off
	s_waitcnt vmcnt(8)
	s_waitcnt lgkmcnt(0)
	s_barrier
	s_setprio 1
	v_mfma_f32_16x16x32_bf16 v[126:129], v[130:133], v[212:215], v[126:129]
	v_mfma_f32_16x16x32_bf16 v[122:125], v[158:161], v[212:215], v[122:125]
	v_mfma_f32_16x16x32_bf16 v[110:113], v[130:133], v[220:223], v[110:113]
	v_mfma_f32_16x16x32_bf16 v[106:109], v[158:161], v[220:223], v[106:109]
	v_mfma_f32_16x16x32_bf16 v[94:97], v[130:133], v[228:231], v[94:97]
	v_mfma_f32_16x16x32_bf16 v[90:93], v[158:161], v[228:231], v[90:93]
	v_mfma_f32_16x16x32_bf16 v[78:81], v[130:133], v[236:239], v[78:81]
	v_mfma_f32_16x16x32_bf16 v[74:77], v[158:161], v[236:239], v[74:77]
	v_mfma_f32_16x16x32_bf16 v[126:129], v[150:153], v[216:219], v[126:129]
	v_mfma_f32_16x16x32_bf16 v[122:125], v[174:177], v[216:219], v[122:125]
	v_mfma_f32_16x16x32_bf16 v[110:113], v[150:153], v[224:227], v[110:113]
	v_mfma_f32_16x16x32_bf16 v[106:109], v[174:177], v[224:227], v[106:109]
	v_mfma_f32_16x16x32_bf16 v[94:97], v[150:153], v[232:235], v[94:97]
	v_mfma_f32_16x16x32_bf16 v[90:93], v[174:177], v[232:235], v[90:93]
	v_mfma_f32_16x16x32_bf16 v[78:81], v[150:153], v[240:243], v[78:81]
	v_mfma_f32_16x16x32_bf16 v[74:77], v[174:177], v[240:243], v[74:77]
	v_mfma_f32_16x16x32_bf16 v[118:121], v[178:181], v[212:215], v[118:121]
	v_mfma_f32_16x16x32_bf16 v[114:117], v[186:189], v[212:215], v[114:117]
	v_mfma_f32_16x16x32_bf16 v[102:105], v[178:181], v[220:223], v[102:105]
	v_mfma_f32_16x16x32_bf16 v[98:101], v[186:189], v[220:223], v[98:101]
	v_mfma_f32_16x16x32_bf16 v[86:89], v[178:181], v[228:231], v[86:89]
	v_mfma_f32_16x16x32_bf16 v[82:85], v[186:189], v[228:231], v[82:85]
	v_mfma_f32_16x16x32_bf16 v[70:73], v[178:181], v[236:239], v[70:73]
	v_mfma_f32_16x16x32_bf16 v[66:69], v[186:189], v[236:239], v[66:69]
	v_mfma_f32_16x16x32_bf16 v[118:121], v[182:185], v[216:219], v[118:121]
	v_mfma_f32_16x16x32_bf16 v[114:117], v[190:193], v[216:219], v[114:117]
	v_mfma_f32_16x16x32_bf16 v[102:105], v[182:185], v[224:227], v[102:105]
	v_mfma_f32_16x16x32_bf16 v[98:101], v[190:193], v[224:227], v[98:101]
	v_mfma_f32_16x16x32_bf16 v[86:89], v[182:185], v[232:235], v[86:89]
	v_mfma_f32_16x16x32_bf16 v[82:85], v[190:193], v[232:235], v[82:85]
	v_mfma_f32_16x16x32_bf16 v[70:73], v[182:185], v[240:243], v[70:73]
	v_mfma_f32_16x16x32_bf16 v[66:69], v[190:193], v[240:243], v[66:69]
	s_setprio 0
	s_barrier
	s_add_i32 s40, s44, s20
	v_lshl_add_u64 v[166:167], v[244:245], 0, s[26:27]
	s_mov_b32 m0, s40
	ds_read_b128 v[212:215], v157 offset:49152
	ds_read_b128 v[216:219], v157 offset:50176
	ds_read_b128 v[220:223], v157 offset:51200
	ds_read_b128 v[224:227], v157 offset:52224
	ds_read_b128 v[228:231], v157 offset:53248
	ds_read_b128 v[232:235], v157 offset:54272
	ds_read_b128 v[236:239], v157 offset:55296
	ds_read_b128 v[240:243], v157 offset:56320
	global_load_lds_dwordx4 v[166:167], off
	s_add_i32 m0, s40, 0x2000
	s_add_u32 s30, s30, 0x40080
	v_lshl_add_u64 v[166:167], v[246:247], 0, s[26:27]
	s_addc_u32 s31, s31, 0
	s_add_i32 s40, s45, s20
	global_load_lds_dwordx4 v[166:167], off
	v_lshl_add_u64 v[166:167], s[30:31], 0, v[136:137]
	s_mov_b32 m0, s40
	s_nop 0
	global_load_lds_dwordx4 v[166:167], off
	v_lshl_add_u64 v[166:167], s[30:31], 0, v[140:141]
	s_add_i32 m0, s40, 0x2000
	s_nop 0
	global_load_lds_dwordx4 v[166:167], off
	v_lshl_add_u64 v[166:167], v[248:249], 0, s[26:27]
	s_mov_b32 m0, s85
	s_nop 0
	global_load_lds_dwordx4 v[166:167], off
	v_lshl_add_u64 v[166:167], v[250:251], 0, s[26:27]
	s_mov_b32 m0, s86
	s_nop 0
	global_load_lds_dwordx4 v[166:167], off
	s_waitcnt vmcnt(8)
	s_waitcnt lgkmcnt(0)
	s_barrier
	s_setprio 1
	v_mfma_f32_16x16x32_bf16 v[62:65], v[130:133], v[212:215], v[62:65]
	v_mfma_f32_16x16x32_bf16 v[58:61], v[158:161], v[212:215], v[58:61]
	v_mfma_f32_16x16x32_bf16 v[46:49], v[130:133], v[220:223], v[46:49]
	v_mfma_f32_16x16x32_bf16 v[42:45], v[158:161], v[220:223], v[42:45]
	v_mfma_f32_16x16x32_bf16 v[30:33], v[130:133], v[228:231], v[30:33]
	v_mfma_f32_16x16x32_bf16 v[26:29], v[158:161], v[228:231], v[26:29]
	v_mfma_f32_16x16x32_bf16 v[14:17], v[130:133], v[236:239], v[14:17]
	v_mfma_f32_16x16x32_bf16 v[10:13], v[158:161], v[236:239], v[10:13]
	v_mfma_f32_16x16x32_bf16 v[62:65], v[150:153], v[216:219], v[62:65]
	v_mfma_f32_16x16x32_bf16 v[58:61], v[174:177], v[216:219], v[58:61]
	v_mfma_f32_16x16x32_bf16 v[46:49], v[150:153], v[224:227], v[46:49]
	v_mfma_f32_16x16x32_bf16 v[42:45], v[174:177], v[224:227], v[42:45]
	v_mfma_f32_16x16x32_bf16 v[30:33], v[150:153], v[232:235], v[30:33]
	v_mfma_f32_16x16x32_bf16 v[26:29], v[174:177], v[232:235], v[26:29]
	v_mfma_f32_16x16x32_bf16 v[14:17], v[150:153], v[240:243], v[14:17]
	v_mfma_f32_16x16x32_bf16 v[10:13], v[174:177], v[240:243], v[10:13]
	v_mfma_f32_16x16x32_bf16 v[54:57], v[178:181], v[212:215], v[54:57]
	v_mfma_f32_16x16x32_bf16 v[50:53], v[186:189], v[212:215], v[50:53]
	v_mfma_f32_16x16x32_bf16 v[38:41], v[178:181], v[220:223], v[38:41]
	v_mfma_f32_16x16x32_bf16 v[34:37], v[186:189], v[220:223], v[34:37]
	v_mfma_f32_16x16x32_bf16 v[22:25], v[178:181], v[228:231], v[22:25]
	v_mfma_f32_16x16x32_bf16 v[18:21], v[186:189], v[228:231], v[18:21]
	v_mfma_f32_16x16x32_bf16 v[6:9], v[178:181], v[236:239], v[6:9]
	v_mfma_f32_16x16x32_bf16 v[2:5], v[186:189], v[236:239], v[2:5]
	v_mfma_f32_16x16x32_bf16 v[54:57], v[182:185], v[216:219], v[54:57]
	v_mfma_f32_16x16x32_bf16 v[50:53], v[190:193], v[216:219], v[50:53]
	v_mfma_f32_16x16x32_bf16 v[38:41], v[182:185], v[224:227], v[38:41]
	v_mfma_f32_16x16x32_bf16 v[34:37], v[190:193], v[224:227], v[34:37]
	v_mfma_f32_16x16x32_bf16 v[22:25], v[182:185], v[232:235], v[22:25]
	v_mfma_f32_16x16x32_bf16 v[18:21], v[190:193], v[232:235], v[18:21]
	v_mfma_f32_16x16x32_bf16 v[6:9], v[182:185], v[240:243], v[6:9]
	v_mfma_f32_16x16x32_bf16 v[2:5], v[190:193], v[240:243], v[2:5]
	s_setprio 0
	s_barrier
	s_add_i32 s43, s43, 2
	s_add_u32 s19, s19, 0x100
	s_addc_u32 s42, s42, 0
	s_add_u32 s14, s14, 0x100
	s_addc_u32 s15, s15, 0
	s_cmp_gt_u32 s43, 13
	s_cbranch_scc0 .LBB0_416
	s_and_b64 vcc, exec, s[10:11]
	v_readlane_b32 s82, v252, 8
	v_readlane_b32 s83, v252, 9
	s_cbranch_vccz .LBB0_419
	s_barrier
